# no s_setprio at all inside the K-loops (flips deleted, no static raise)
# baseline (speedup 1.0000x reference)
.LBB0_169:
	s_ashr_i32 s51, s50, 31
	s_lshl_b64 s[12:13], s[50:51], 19
	s_add_u32 s52, s17, s12
	s_addc_u32 s53, s60, s13
	s_and_b64 s[12:13], s[40:41], exec
	s_cselect_b32 s3, s53, s9
	s_cselect_b32 s24, s52, s8
	s_ashr_i32 s49, s48, 31
	s_lshl_b64 s[12:13], s[48:49], 19
	s_add_u32 s54, s82, s12
	s_addc_u32 s55, s83, s13
	s_and_b64 s[12:13], s[40:41], exec
	s_cselect_b32 s25, s55, s11
	s_cselect_b32 s26, s54, s10
	s_add_u32 s8, s8, 0x40080
	s_addc_u32 s9, s9, 0
	s_add_u32 s27, s10, 0x100
	v_mov_b32_e32 v2, 0
	s_addc_u32 s28, s11, 0
	s_mov_b32 s29, -2
	v_mov_b64_e32 v[2:3], 0
	v_mov_b64_e32 v[4:5], 0
	v_mov_b64_e32 v[6:7], 0
	v_mov_b64_e32 v[8:9], 0
	v_mov_b64_e32 v[10:11], 0
	v_mov_b64_e32 v[12:13], 0
	v_mov_b64_e32 v[14:15], 0
	v_mov_b64_e32 v[16:17], 0
	v_mov_b64_e32 v[18:19], 0
	v_mov_b64_e32 v[20:21], 0
	v_mov_b64_e32 v[22:23], 0
	v_mov_b64_e32 v[24:25], 0
	v_mov_b64_e32 v[26:27], 0
	v_mov_b64_e32 v[28:29], 0
	v_mov_b64_e32 v[30:31], 0
	v_mov_b64_e32 v[32:33], 0
	v_mov_b64_e32 v[34:35], 0
	v_mov_b64_e32 v[36:37], 0
	v_mov_b64_e32 v[38:39], 0
	v_mov_b64_e32 v[40:41], 0
	v_mov_b64_e32 v[42:43], 0
	v_mov_b64_e32 v[44:45], 0
	v_mov_b64_e32 v[46:47], 0
	v_mov_b64_e32 v[48:49], 0
	v_mov_b64_e32 v[50:51], 0
	v_mov_b64_e32 v[52:53], 0
	v_mov_b64_e32 v[54:55], 0
	v_mov_b64_e32 v[56:57], 0
	v_mov_b64_e32 v[58:59], 0
	v_mov_b64_e32 v[60:61], 0
	v_mov_b64_e32 v[62:63], 0
	v_mov_b64_e32 v[64:65], 0
	v_mov_b64_e32 v[66:67], 0
	v_mov_b64_e32 v[68:69], 0
	v_mov_b64_e32 v[70:71], 0
	v_mov_b64_e32 v[72:73], 0
	v_mov_b64_e32 v[74:75], 0
	v_mov_b64_e32 v[76:77], 0
	v_mov_b64_e32 v[78:79], 0
	v_mov_b64_e32 v[80:81], 0
	v_mov_b64_e32 v[82:83], 0
	v_mov_b64_e32 v[84:85], 0
	v_mov_b64_e32 v[86:87], 0
	v_mov_b64_e32 v[88:89], 0
	v_mov_b64_e32 v[90:91], 0
	v_mov_b64_e32 v[92:93], 0
	v_mov_b64_e32 v[94:95], 0
	v_mov_b64_e32 v[96:97], 0
	v_mov_b64_e32 v[98:99], 0
	v_mov_b64_e32 v[100:101], 0
	v_mov_b64_e32 v[102:103], 0
	v_mov_b64_e32 v[104:105], 0
	v_mov_b64_e32 v[106:107], 0
	v_mov_b64_e32 v[108:109], 0
	v_mov_b64_e32 v[110:111], 0
	v_mov_b64_e32 v[112:113], 0
	v_mov_b64_e32 v[114:115], 0
	v_mov_b64_e32 v[116:117], 0
	v_mov_b64_e32 v[118:119], 0
	v_mov_b64_e32 v[120:121], 0
	v_mov_b64_e32 v[122:123], 0
	v_mov_b64_e32 v[124:125], 0
	v_mov_b64_e32 v[126:127], 0
	v_mov_b64_e32 v[128:129], 0
.Lprio_LBB0_170:
.LBB0_170:
	s_add_u32 s10, s8, 0xfffc0080
	s_addc_u32 s11, s9, -1
	s_add_i32 s30, 0, 0x10000
	s_cmp_eq_u32 s29, 12
	s_cselect_b32 s13, s3, s11
	s_cselect_b32 s12, s24, s10
	s_cselect_b32 s11, s25, s28
	s_cselect_b32 s10, s26, s27
	s_add_i32 s31, 0, 0x14000
	.p2align	8

.LBB0_545:
	s_ashr_i32 s47, s46, 31
	s_lshl_b64 s[14:15], s[46:47], 19
	s_add_u32 s48, s74, s14
	s_addc_u32 s49, s75, s15
	s_and_b64 s[14:15], s[40:41], exec
	s_cselect_b32 s14, s49, s53
	s_cselect_b32 s15, s48, s52
	s_ashr_i32 s45, s44, 31
	s_lshl_b64 s[24:25], s[44:45], 19
	s_add_u32 s50, s0, s24
	s_addc_u32 s51, s1, s25
	s_and_b64 s[24:25], s[40:41], exec
	s_cselect_b32 s26, s51, s11
	s_cselect_b32 s27, s50, s10
	s_lshl_b32 s24, s12, 8
	s_lshl_b32 s25, s13, 8
	s_or_b32 s28, s25, s63
	s_add_i32 s29, s24, s62
	s_add_u32 s12, s52, 0x40080
	s_addc_u32 s13, s53, 0
	v_mov_b32_e32 v2, v1
	v_mov_b32_e32 v3, v1
	s_add_u32 s45, s10, 0x100
	v_mov_b32_e32 v0, v1
	v_mov_b64_e32 v[6:7], v[2:3]
	v_mov_b64_e32 v[10:11], v[2:3]
	v_mov_b64_e32 v[22:23], v[2:3]
	v_mov_b64_e32 v[26:27], v[2:3]
	v_mov_b64_e32 v[38:39], v[2:3]
	v_mov_b64_e32 v[42:43], v[2:3]
	v_mov_b64_e32 v[54:55], v[2:3]
	v_mov_b64_e32 v[58:59], v[2:3]
	v_mov_b64_e32 v[14:15], v[2:3]
	v_mov_b64_e32 v[18:19], v[2:3]
	v_mov_b64_e32 v[30:31], v[2:3]
	v_mov_b64_e32 v[34:35], v[2:3]
	v_mov_b64_e32 v[46:47], v[2:3]
	v_mov_b64_e32 v[50:51], v[2:3]
	v_mov_b64_e32 v[62:63], v[2:3]
	v_mov_b64_e32 v[66:67], v[2:3]
	v_mov_b64_e32 v[70:71], v[2:3]
	v_mov_b64_e32 v[74:75], v[2:3]
	v_mov_b64_e32 v[86:87], v[2:3]
	v_mov_b64_e32 v[90:91], v[2:3]
	v_mov_b64_e32 v[102:103], v[2:3]
	v_mov_b64_e32 v[106:107], v[2:3]
	v_mov_b64_e32 v[118:119], v[2:3]
	v_mov_b64_e32 v[122:123], v[2:3]
	v_mov_b64_e32 v[78:79], v[2:3]
	v_mov_b64_e32 v[82:83], v[2:3]
	v_mov_b64_e32 v[94:95], v[2:3]
	v_mov_b64_e32 v[98:99], v[2:3]
	v_mov_b64_e32 v[110:111], v[2:3]
	v_mov_b64_e32 v[114:115], v[2:3]
	v_mov_b64_e32 v[126:127], v[2:3]
	v_mov_b64_e32 v[130:131], v[2:3]
	v_lshl_add_u64 v[154:155], s[12:13], 0, v[144:145]
	v_lshl_add_u64 v[156:157], s[12:13], 0, v[152:153]
	s_addc_u32 s47, s11, 0
	s_mov_b32 s68, -2
	s_mov_b64 s[10:11], 0
	v_mov_b64_e32 v[4:5], v[0:1]
	v_mov_b64_e32 v[8:9], v[0:1]
	v_mov_b64_e32 v[20:21], v[0:1]
	v_mov_b64_e32 v[24:25], v[0:1]
	v_mov_b64_e32 v[36:37], v[0:1]
	v_mov_b64_e32 v[40:41], v[0:1]
	v_mov_b64_e32 v[52:53], v[0:1]
	v_mov_b64_e32 v[56:57], v[0:1]
	v_mov_b64_e32 v[12:13], v[0:1]
	v_mov_b64_e32 v[16:17], v[0:1]
	v_mov_b64_e32 v[28:29], v[0:1]
	v_mov_b64_e32 v[32:33], v[0:1]
	v_mov_b64_e32 v[44:45], v[0:1]
	v_mov_b64_e32 v[48:49], v[0:1]
	v_mov_b64_e32 v[60:61], v[0:1]
	v_mov_b64_e32 v[64:65], v[0:1]
	v_mov_b64_e32 v[68:69], v[0:1]
	v_mov_b64_e32 v[72:73], v[0:1]
	v_mov_b64_e32 v[84:85], v[0:1]
	v_mov_b64_e32 v[88:89], v[0:1]
	v_mov_b64_e32 v[100:101], v[0:1]
	v_mov_b64_e32 v[104:105], v[0:1]
	v_mov_b64_e32 v[116:117], v[0:1]
	v_mov_b64_e32 v[120:121], v[0:1]
	v_mov_b64_e32 v[76:77], v[0:1]
	v_mov_b64_e32 v[80:81], v[0:1]
	v_mov_b64_e32 v[92:93], v[0:1]
	v_mov_b64_e32 v[96:97], v[0:1]
	v_mov_b64_e32 v[108:109], v[0:1]
	v_mov_b64_e32 v[112:113], v[0:1]
	v_mov_b64_e32 v[124:125], v[0:1]
	v_mov_b64_e32 v[128:129], v[0:1]
.Lprio_LBB0_546:
	s_branch .LBB0_547

.LBB0_639:
	s_ashr_i32 s49, s48, 31
	s_lshl_b64 s[14:15], s[48:49], 19
	v_readlane_b32 s11, v254, 16
	s_add_u32 s50, s11, s14
	v_readlane_b32 s11, v254, 17
	s_addc_u32 s51, s11, s15
	s_and_b64 s[14:15], s[42:43], exec
	s_cselect_b32 s11, s51, s13
	s_cselect_b32 s14, s50, s12
	s_ashr_i32 s47, s46, 31
	s_lshl_b64 s[24:25], s[46:47], 19
	s_add_u32 s52, s74, s24
	s_addc_u32 s53, s75, s25
	s_and_b64 s[24:25], s[42:43], exec
	s_cselect_b32 s15, s53, s55
	s_cselect_b32 s24, s52, s54
	s_add_u32 s12, s12, 0x40080
	s_addc_u32 s13, s13, 0
	s_add_u32 s25, s54, 0x100
	v_mov_b32_e32 v0, 0
	s_addc_u32 s26, s55, 0
	s_mov_b32 s27, -2
	s_waitcnt lgkmcnt(0)
	v_mov_b64_e32 v[0:1], 0
	v_mov_b64_e32 v[2:3], 0
	v_mov_b64_e32 v[4:5], 0
	v_mov_b64_e32 v[6:7], 0
	v_mov_b64_e32 v[8:9], 0
	v_mov_b64_e32 v[10:11], 0
	v_mov_b64_e32 v[12:13], 0
	v_mov_b64_e32 v[14:15], 0
	v_mov_b64_e32 v[16:17], 0
	v_mov_b64_e32 v[18:19], 0
	v_mov_b64_e32 v[20:21], 0
	v_mov_b64_e32 v[22:23], 0
	v_mov_b64_e32 v[24:25], 0
	v_mov_b64_e32 v[26:27], 0
	v_mov_b64_e32 v[28:29], 0
	v_mov_b64_e32 v[30:31], 0
	v_mov_b64_e32 v[32:33], 0
	v_mov_b64_e32 v[34:35], 0
	v_mov_b64_e32 v[36:37], 0
	v_mov_b64_e32 v[38:39], 0
	v_mov_b64_e32 v[40:41], 0
	v_mov_b64_e32 v[42:43], 0
	v_mov_b64_e32 v[44:45], 0
	v_mov_b64_e32 v[46:47], 0
	v_mov_b64_e32 v[48:49], 0
	v_mov_b64_e32 v[50:51], 0
	v_mov_b64_e32 v[52:53], 0
	v_mov_b64_e32 v[54:55], 0
	v_mov_b64_e32 v[56:57], 0
	v_mov_b64_e32 v[58:59], 0
	v_mov_b64_e32 v[60:61], 0
	v_mov_b64_e32 v[62:63], 0
	v_mov_b64_e32 v[64:65], 0
	v_mov_b64_e32 v[66:67], 0
	v_mov_b64_e32 v[68:69], 0
	v_mov_b64_e32 v[70:71], 0
	v_mov_b64_e32 v[72:73], 0
	v_mov_b64_e32 v[74:75], 0
	v_mov_b64_e32 v[76:77], 0
	v_mov_b64_e32 v[78:79], 0
	v_mov_b64_e32 v[80:81], 0
	v_mov_b64_e32 v[82:83], 0
	v_mov_b64_e32 v[84:85], 0
	v_mov_b64_e32 v[86:87], 0
	v_mov_b64_e32 v[88:89], 0
	v_mov_b64_e32 v[90:91], 0
	v_mov_b64_e32 v[92:93], 0
	v_mov_b64_e32 v[94:95], 0
	v_mov_b64_e32 v[96:97], 0
	v_mov_b64_e32 v[98:99], 0
	v_mov_b64_e32 v[100:101], 0
	v_mov_b64_e32 v[102:103], 0
	v_mov_b64_e32 v[104:105], 0
	v_mov_b64_e32 v[106:107], 0
	v_mov_b64_e32 v[108:109], 0
	v_mov_b64_e32 v[110:111], 0
	v_mov_b64_e32 v[112:113], 0
	v_mov_b64_e32 v[114:115], 0
	v_mov_b64_e32 v[116:117], 0
	v_mov_b64_e32 v[118:119], 0
	v_mov_b64_e32 v[120:121], 0
	v_mov_b64_e32 v[122:123], 0
	v_mov_b64_e32 v[124:125], 0
	v_mov_b64_e32 v[126:127], 0
.Lprio_LBB0_640:
	.p2align	8

.LBB0_743:
	s_ashr_i32 s81, s80, 31
	s_lshl_b64 s[14:15], s[80:81], 19
	s_add_u32 s82, s96, s14
	s_addc_u32 s83, s97, s15
	s_and_b64 s[14:15], s[44:45], exec
	s_cselect_b32 s11, s83, s47
	s_cselect_b32 s14, s82, s46
	s_ashr_i32 s75, s74, 31
	s_lshl_b64 s[16:17], s[74:75], 19
	v_readlane_b32 s24, v254, 6
	v_readlane_b32 s25, v254, 7
	s_add_u32 s84, s24, s16
	s_addc_u32 s85, s25, s17
	s_and_b64 s[16:17], s[44:45], exec
	s_cselect_b32 s15, s85, s49
	s_cselect_b32 s16, s84, s48
	s_add_u32 s46, s46, 0x40080
	s_addc_u32 s47, s47, 0
	s_add_u32 s17, s48, 0x100
	v_mov_b32_e32 v64, 0
	s_addc_u32 s24, s49, 0
	s_mov_b32 s25, -2
	v_mov_b64_e32 v[0:1], 0
	v_mov_b64_e32 v[2:3], 0
	v_mov_b64_e32 v[4:5], 0
	v_mov_b64_e32 v[6:7], 0
	v_mov_b64_e32 v[8:9], 0
	v_mov_b64_e32 v[10:11], 0
	v_mov_b64_e32 v[12:13], 0
	v_mov_b64_e32 v[14:15], 0
	v_mov_b64_e32 v[16:17], 0
	v_mov_b64_e32 v[18:19], 0
	v_mov_b64_e32 v[20:21], 0
	v_mov_b64_e32 v[22:23], 0
	v_mov_b64_e32 v[24:25], 0
	v_mov_b64_e32 v[26:27], 0
	v_mov_b64_e32 v[28:29], 0
	v_mov_b64_e32 v[30:31], 0
	v_mov_b64_e32 v[32:33], 0
	v_mov_b64_e32 v[34:35], 0
	v_mov_b64_e32 v[36:37], 0
	v_mov_b64_e32 v[38:39], 0
	v_mov_b64_e32 v[40:41], 0
	v_mov_b64_e32 v[42:43], 0
	v_mov_b64_e32 v[44:45], 0
	v_mov_b64_e32 v[46:47], 0
	v_mov_b64_e32 v[48:49], 0
	v_mov_b64_e32 v[50:51], 0
	v_mov_b64_e32 v[52:53], 0
	v_mov_b64_e32 v[54:55], 0
	v_mov_b64_e32 v[56:57], 0
	v_mov_b64_e32 v[58:59], 0
	v_mov_b64_e32 v[60:61], 0
	v_mov_b64_e32 v[62:63], 0
	v_mov_b64_e32 v[64:65], 0
	v_mov_b64_e32 v[66:67], 0
	v_mov_b64_e32 v[68:69], 0
	v_mov_b64_e32 v[70:71], 0
	v_mov_b64_e32 v[72:73], 0
	v_mov_b64_e32 v[74:75], 0
	v_mov_b64_e32 v[76:77], 0
	v_mov_b64_e32 v[78:79], 0
	v_mov_b64_e32 v[96:97], 0
	v_mov_b64_e32 v[98:99], 0
	v_mov_b64_e32 v[100:101], 0
	v_mov_b64_e32 v[102:103], 0
	v_mov_b64_e32 v[104:105], 0
	v_mov_b64_e32 v[106:107], 0
	v_mov_b64_e32 v[108:109], 0
	v_mov_b64_e32 v[110:111], 0
	v_mov_b64_e32 v[112:113], 0
	v_mov_b64_e32 v[114:115], 0
	v_mov_b64_e32 v[116:117], 0
	v_mov_b64_e32 v[118:119], 0
	v_mov_b64_e32 v[120:121], 0
	v_mov_b64_e32 v[122:123], 0
	v_mov_b64_e32 v[124:125], 0
	v_mov_b64_e32 v[126:127], 0
	v_mov_b64_e32 v[136:137], 0
	v_mov_b64_e32 v[138:139], 0
	v_mov_b64_e32 v[140:141], 0
	v_mov_b64_e32 v[142:143], 0
	v_mov_b64_e32 v[144:145], 0
	v_mov_b64_e32 v[146:147], 0
	v_mov_b64_e32 v[148:149], 0
	v_mov_b64_e32 v[150:151], 0
.Lprio_LBB0_744:
	.p2align	8

.LBB0_954:
	s_add_u32 s13, s46, 0x100
	v_mov_b32_e32 v0, 0
	s_addc_u32 s14, s47, 0
	s_mov_b32 s15, -2
	v_mov_b64_e32 v[0:1], 0
	v_mov_b64_e32 v[2:3], 0
	v_mov_b64_e32 v[4:5], 0
	v_mov_b64_e32 v[6:7], 0
	v_mov_b64_e32 v[8:9], 0
	v_mov_b64_e32 v[10:11], 0
	v_mov_b64_e32 v[12:13], 0
	v_mov_b64_e32 v[14:15], 0
	v_mov_b64_e32 v[16:17], 0
	v_mov_b64_e32 v[18:19], 0
	v_mov_b64_e32 v[20:21], 0
	v_mov_b64_e32 v[22:23], 0
	v_mov_b64_e32 v[24:25], 0
	v_mov_b64_e32 v[26:27], 0
	v_mov_b64_e32 v[28:29], 0
	v_mov_b64_e32 v[30:31], 0
	v_mov_b64_e32 v[32:33], 0
	v_mov_b64_e32 v[34:35], 0
	v_mov_b64_e32 v[36:37], 0
	v_mov_b64_e32 v[38:39], 0
	v_mov_b64_e32 v[40:41], 0
	v_mov_b64_e32 v[42:43], 0
	v_mov_b64_e32 v[44:45], 0
	v_mov_b64_e32 v[46:47], 0
	v_mov_b64_e32 v[48:49], 0
	v_mov_b64_e32 v[50:51], 0
	v_mov_b64_e32 v[52:53], 0
	v_mov_b64_e32 v[54:55], 0
	v_mov_b64_e32 v[56:57], 0
	v_mov_b64_e32 v[58:59], 0
	v_mov_b64_e32 v[60:61], 0
	v_mov_b64_e32 v[62:63], 0
	v_mov_b64_e32 v[64:65], 0
	v_mov_b64_e32 v[66:67], 0
	v_mov_b64_e32 v[68:69], 0
	v_mov_b64_e32 v[70:71], 0
	v_mov_b64_e32 v[72:73], 0
	v_mov_b64_e32 v[74:75], 0
	v_mov_b64_e32 v[76:77], 0
	v_mov_b64_e32 v[78:79], 0
	v_mov_b64_e32 v[80:81], 0
	v_mov_b64_e32 v[82:83], 0
	v_mov_b64_e32 v[84:85], 0
	v_mov_b64_e32 v[86:87], 0
	v_mov_b64_e32 v[88:89], 0
	v_mov_b64_e32 v[90:91], 0
	v_mov_b64_e32 v[92:93], 0
	v_mov_b64_e32 v[94:95], 0
	v_mov_b64_e32 v[96:97], 0
	v_mov_b64_e32 v[98:99], 0
	v_mov_b64_e32 v[100:101], 0
	v_mov_b64_e32 v[102:103], 0
	v_mov_b64_e32 v[104:105], 0
	v_mov_b64_e32 v[106:107], 0
	v_mov_b64_e32 v[108:109], 0
	v_mov_b64_e32 v[110:111], 0
	v_mov_b64_e32 v[112:113], 0
	v_mov_b64_e32 v[114:115], 0
	v_mov_b64_e32 v[116:117], 0
	v_mov_b64_e32 v[118:119], 0
	v_mov_b64_e32 v[120:121], 0
	v_mov_b64_e32 v[122:123], 0
	v_mov_b64_e32 v[124:125], 0
	v_mov_b64_e32 v[126:127], 0
.Lprio_LBB0_955:
	.p2align	8
